# gemm4 K=1024 gate GEMM loop also converted to the BK=64 full-line double-buffered form (register-tight variant: B fragments of the second k-half reuse the first half's registers)
# speedup vs baseline: 1.1266x; 1.0050x over previous
; __device__ __forceinline__ int tid_() { int t = threadIdx.x; asm volatile("" : "+v"(t)); return t; }
; #define ZERO_ACC(acc) zero_acc(acc)
; __device__ __forceinline__ void gemm_issue(const GemmOps& g, int kt, int buf, char* L) {
;   const int wid = tid_() >> 6;
;   char* sb = L + buf * GEMM_STAGE_B;
;   __builtin_amdgcn_global_load_lds((const unsigned*)(g.a0 + kt * 32), (unsigned*)(sb + wid * 1024), 16, 0, 0);
;   __builtin_amdgcn_global_load_lds((const unsigned*)(g.a1 + kt * 32), (unsigned*)(sb + (wid + 4) * 1024), 16, 0, 0);
;   __builtin_amdgcn_global_load_lds((const unsigned*)(g.b0 + kt * 32), (unsigned*)(sb + 8192 + wid * 1024), 16, 0, 0);
;   __builtin_amdgcn_global_load_lds((const unsigned*)(g.b1 + kt * 32), (unsigned*)(sb + 8192 + (wid + 4) * 1024), 16, 0, 0);
; }
; __device__ __forceinline__ void gemm_prologue(const GemmOps& g, u16* lds) {
;   gemm_issue(g, 0, 0, (char*)lds); gemm_issue(g, 1, 1, (char*)lds);
; __device__ void ph_gemm4(const P& p, u16* lds) {
;   const int lane = tid_() & 63, wid = tid_() >> 6, wm = wid >> 1, wn = wid & 1, fq = lane >> 4;
;   const int NT = 8, NTILES = 264 * NT;
;   int it = blockIdx.x;
;   if (it >= NTILES) return;
;   auto opsP = [&](int t) __attribute__((always_inline)) { return gemm_ops(p_Pb + (size_t)(t / NT) * 128 * 256, 256, p_WpT + (size_t)(t % NT) * 128 * 256, 256); };
;   auto opsG = [&](int t) __attribute__((always_inline)) { return gemm_ops(p_Abf + (size_t)(t / NT) * 128 * DM, DM, p_WgT + (size_t)(t % NT) * 128 * DM, DM); };
;   GemmOps g = opsP(it);
;   __syncthreads();
;   gemm_prologue(g, lds);
;   while (true) {
;     const int mt = it / NT, nt = it % NT;
;     f32x4 acc[4][4]; ZERO_ACC(acc);
;     gemm_main(acc, g, 256, lds);
.LBB0_1109:
	s_cmp_lt_i32 s6, 13
	s_cselect_b64 s[0:1], -1, 0
	s_cmp_gt_i32 s7, 12
	s_cselect_b64 s[2:3], -1, 0
	s_and_b64 s[0:1], s[0:1], s[2:3]
	s_andn2_b64 vcc, exec, s[0:1]
	s_cbranch_vccnz .LBB0_1171
	v_readlane_b32 s0, v228, 0
	s_waitcnt vmcnt(0)
	v_mov_b32_e32 v0, v220
	s_waitcnt lgkmcnt(0)
	v_mov_b32_e32 v1, v220
	s_cmpk_gt_i32 s0, 0x83f
	v_readlane_b32 s1, v228, 1
	s_cbranch_scc1 .LBB0_1117
	v_readlane_b32 s0, v228, 2
	v_readlane_b32 s4, v228, 6
	v_readlane_b32 s5, v228, 7
	v_readlane_b32 s6, v228, 8
	v_readlane_b32 s7, v228, 9
	s_add_u32 s33, s6, 0x2ec0000
	v_readlane_b32 s4, v228, 0
	s_addc_u32 s45, s7, 0
	s_and_b32 s81, s4, 7
	s_lshr_b32 s82, s4, 3
	s_lshr_b32 s83, s82, 6
	s_and_b32 s84, s82, 63
	s_cmp_lt_u32 s83, 4
	s_cselect_b32 s85, 3, 0
	s_cselect_b32 s86, 7, 0
	s_lshr_b32 s87, s84, s85
	s_and_b32 s84, s84, s86
	s_lshl_b32 s83, s83, 3
	s_add_u32 s83, s83, s84
	s_mul_i32 s81, s81, 33
	s_add_u32 s81, s81, s83
	s_mul_i32 s81, s81, 8
	s_add_u32 s80, s81, s87
	s_ashr_i32 s0, s80, 31
	v_readlane_b32 s2, v228, 4
	s_lshr_b32 s0, s0, 29
	s_add_i32 s2, s80, s0
	v_readlane_b32 s1, v228, 3
	s_ashr_i32 s0, s2, 3
	s_ashr_i32 s1, s0, 31
	s_lshl_b64 s[0:1], s[0:1], 16
	s_add_u32 s0, s33, s0
	s_addc_u32 s1, s45, s1
	s_add_u32 s47, s6, 0xdc0000
	s_addc_u32 s52, s7, 0
	s_and_b32 s2, s2, -8
	v_mov_b32_e32 v5, v220
	v_mov_b32_e32 v2, v220
	v_readlane_b32 s3, v228, 5
	s_sub_i32 s2, s80, s2
	s_ashr_i32 s3, s2, 31
	v_lshrrev_b32_e32 v3, 2, v5
	v_ashrrev_i32_e32 v2, 2, v2
	v_lshrrev_b32_e32 v8, 4, v5
	s_lshl_b64 s[2:3], s[2:3], 16
	v_bfi_b32 v2, -16, v2, v3
	v_xor_b32_e32 v5, v8, v5
	s_add_u32 s2, s47, s2
	v_add_u32_e32 v4, 64, v2
	v_ashrrev_i32_e32 v3, 31, v2
	v_lshlrev_b32_e32 v5, 4, v5
	s_addc_u32 s3, s52, s3
	v_lshlrev_b64 v[2:3], 9, v[2:3]
	v_and_b32_e32 v128, 48, v5
	v_ashrrev_i32_e32 v5, 31, v4
	v_lshl_add_u64 v[6:7], s[0:1], 0, v[2:3]
	v_mov_b32_e32 v129, 0
	v_lshlrev_b64 v[4:5], 9, v[4:5]
	v_lshl_add_u64 v[2:3], s[2:3], 0, v[2:3]
	v_lshl_add_u64 v[134:135], v[2:3], 0, v[128:129]
	v_lshl_add_u64 v[2:3], s[2:3], 0, v[4:5]
	v_lshl_add_u64 v[136:137], v[2:3], 0, v[128:129]
	v_mov_b32_e32 v2, v220
	s_barrier
	v_lshl_add_u64 v[130:131], v[6:7], 0, v[128:129]
	v_lshlrev_b32_e32 v2, 4, v2
	v_and_b32_e32 v2, 0xfffffc00, v2
	v_lshl_add_u64 v[6:7], s[0:1], 0, v[4:5]
	v_readfirstlane_b32 s0, v2
	v_add_u32_e32 v3, 0x1000, v2
	s_mov_b32 m0, s0
	v_readfirstlane_b32 s0, v3
	v_add_u32_e32 v3, 0x2000, v2
	v_lshl_add_u64 v[132:133], v[6:7], 0, v[128:129]
	global_load_lds_dwordx4 v[130:131], off
	s_mov_b32 m0, s0
	v_readfirstlane_b32 s0, v3
	v_add_u32_e32 v2, 0x3000, v2
	global_load_lds_dwordx4 v[132:133], off
	s_mov_b32 m0, s0
	v_readfirstlane_b32 s0, v2
	global_load_lds_dwordx4 v[134:135], off
	s_mov_b32 m0, s0
	v_mov_b32_e32 v4, v220
	global_load_lds_dwordx4 v[136:137], off
	v_lshl_add_u64 v[2:3], v[130:131], 0, 64
	v_lshlrev_b32_e32 v4, 4, v4
	v_and_b32_e32 v4, 0xfffffc00, v4
	v_add_u32_e32 v5, 0x4000, v4
	s_add_u32 s53, s6, 0x3f40000
	v_readfirstlane_b32 s0, v5
	v_add_u32_e32 v5, 0x5000, v4
	s_mov_b32 m0, s0
	v_readfirstlane_b32 s0, v5
	v_add_u32_e32 v5, 0x6000, v4
	global_load_lds_dwordx4 v[2:3], off
	v_lshl_add_u64 v[2:3], v[132:133], 0, 64
	s_mov_b32 m0, s0
	v_readfirstlane_b32 s0, v5
	v_add_u32_e32 v4, 0x7000, v4
	global_load_lds_dwordx4 v[2:3], off
	v_lshl_add_u64 v[2:3], v[134:135], 0, 64
	s_mov_b32 m0, s0
	v_readfirstlane_b32 s0, v4
	global_load_lds_dwordx4 v[2:3], off
	v_lshl_add_u64 v[2:3], v[136:137], 0, 64
	s_mov_b32 m0, s0
	s_addc_u32 s54, s7, 0
	global_load_lds_dwordx4 v[2:3], off
	s_add_u32 s55, s6, 0xbc0000
	s_addc_u32 s56, s7, 0
	s_add_u32 s2, s6, 0x179cc000
	v_and_b32_e32 v146, 64, v1
	v_ashrrev_i32_e32 v1, 1, v1
	s_addc_u32 s3, s7, 0
	v_and_b32_e32 v147, 0xffffffc0, v1
	v_lshrrev_b32_e32 v0, 2, v0
	s_add_u32 s16, s6, 0x1ba11600
	v_and_or_b32 v148, v0, 12, v147
	v_or_b32_e32 v149, 16, v147
	v_or_b32_e32 v150, 20, v147
	v_or_b32_e32 v151, 24, v147
	v_or_b32_e32 v152, 28, v147
	v_or_b32_e32 v153, 32, v147
	v_or_b32_e32 v154, 36, v147
	v_or_b32_e32 v155, 40, v147
	v_or_b32_e32 v156, 44, v147
	v_or_b32_e32 v157, 48, v147
	v_or_b32_e32 v158, 52, v147
	v_or_b32_e32 v159, 56, v147
	v_or_b32_e32 v160, 60, v147
	s_addc_u32 s17, s7, 0
	s_mov_b32 s57, 0x3ffffc0
	s_movk_i32 s58, 0x13c0
	s_mov_b64 s[18:19], 0x80
	s_mov_b64 s[20:21], 0xc0
	s_mov_b64 s[22:23], 0x100
	s_mov_b64 s[24:25], 0x140
	s_mov_b64 s[26:27], 0x180
	s_mov_b64 s[28:29], 0x1c0
	s_mov_b64 s[30:31], 0x3f40080
	s_mov_b64 s[34:35], 0xbc0080
	s_mov_b64 s[36:37], 0x3f400c0
	s_mov_b64 s[38:39], 0xbc00c0
	s_mov_b64 s[40:41], 0x3f40100
	s_mov_b64 s[42:43], 0xbc0100
	s_mov_b32 s44, 0x3a800000
	s_mov_b32 s46, 0x358637bd
	s_mov_b32 s59, 0x800000
	s_movk_i32 s60, 0x1100
	s_movk_i32 s61, 0x110
	s_movk_i32 s68, 0x440
	s_mov_b32 s69, s4
	v_readlane_b32 s5, v228, 1
	v_lshrrev_b32_e32 v206, 3, v220
	v_lshlrev_b32_e32 v206, 11, v206
	v_bfe_u32 v207, v220, 4, 3
	v_and_b32_e32 v208, 7, v220
	v_xor_b32_e32 v207, v207, v208
	v_lshl_add_u32 v206, v207, 4, v206
	v_add_u32_e32 v207, 0x10000, v206
	v_add_u32_e32 v208, 0x20000, v206
	v_add_u32_e32 v209, 0x30000, v206
	v_and_b32_e32 v216, 15, v220
	v_bfe_u32 v217, v220, 4, 2
	v_bfe_u32 v218, v220, 1, 3
	v_xor_b32_e32 v217, v217, v218
	v_lshlrev_b32_e32 v217, 4, v217
	v_lshl_add_u32 v216, v216, 7, v217
	v_lshrrev_b32_e32 v217, 7, v220
	v_lshl_add_u32 v210, v217, 13, v216
	v_xor_b32_e32 v211, 64, v210
	v_bfe_u32 v217, v220, 6, 1
	v_lshl_add_u32 v212, v217, 13, v216
	v_add_u32_e32 v212, 0x4000, v212
	v_xor_b32_e32 v213, 64, v212
	v_lshl_add_u32 v214, v217, 10, v212
	v_lshl_add_u32 v215, v217, 10, v213
	v_readfirstlane_b32 s92, v220
	s_nop 0
	s_lshl_b32 s92, s92, 4
	s_add_u32 s93, s92, 0x8000
	s_branch .LBB0_1113

; __device__ __forceinline__ int tid_() { int t = threadIdx.x; asm volatile("" : "+v"(t)); return t; }
; __device__ __forceinline__ f32x4 mfma16(bf16x8 a, bf16x8 b, f32x4 c) { return __builtin_amdgcn_mfma_f32_16x16x32_bf16(a, b, c, 0, 0, 0); }
; #define GEMM_STEP(J, BUF, NBUF) do { asm volatile("s_waitcnt vmcnt(4)" ::: "memory"); RAW_BARRIER(); \
;     if ((J) + 2 < nk) gemm_issue(g, (J) + 2, NBUF, L); comp(BUF); } while (0)
; __device__ __forceinline__ void gemm_issue(const GemmOps& g, int kt, int buf, char* L) {
;   const int wid = tid_() >> 6;
;   char* sb = L + buf * GEMM_STAGE_B;
;   __builtin_amdgcn_global_load_lds((const unsigned*)(g.a0 + kt * 32), (unsigned*)(sb + wid * 1024), 16, 0, 0);
;   __builtin_amdgcn_global_load_lds((const unsigned*)(g.a1 + kt * 32), (unsigned*)(sb + (wid + 4) * 1024), 16, 0, 0);
;   __builtin_amdgcn_global_load_lds((const unsigned*)(g.b0 + kt * 32), (unsigned*)(sb + 8192 + wid * 1024), 16, 0, 0);
;   __builtin_amdgcn_global_load_lds((const unsigned*)(g.b1 + kt * 32), (unsigned*)(sb + 8192 + (wid + 4) * 1024), 16, 0, 0);
; __device__ __forceinline__ void gemm_main(f32x4 (&acc)[4][4], const GemmOps& g, int K, u16* lds) {
;     ...
;   auto comp = [&](int buf) __attribute__((always_inline)) {
;     const char* sb = L + buf * GEMM_STAGE_B;
;     bf16x8 a[4], b[4];
; #pragma unroll
;     for (int i = 0; i < 4; ++i) a[i] = *(const bf16x8*)(sb + offA[i]);
; #pragma unroll
;     for (int j = 0; j < 4; ++j) b[j] = *(const bf16x8*)(sb + offB[j]);
; #pragma unroll
;     for (int i = 0; i < 4; ++i)
; #pragma unroll
;       for (int j = 0; j < 4; ++j) acc[i][j] = mfma16(a[i], b[j], acc[i][j]);
;   };
;   const int nk = K >> 5;
;     ...
;   int j = 0;
;   for (; j + 3 <= nk - 1; j += 3) {
;     GEMM_STEP(j, 0, 2);
;     GEMM_STEP(j + 1, 1, 0);
;     GEMM_STEP(j + 2, 2, 1);
;   }
;   GEMM_STEP(j, 0, 2);
.LBB0_1113:
	v_mov_b32_e32 v4, v220
	s_waitcnt vmcnt(4)
	s_waitcnt lgkmcnt(0)
	s_barrier
	v_lshlrev_b32_e32 v2, 2, v4
	v_bitop3_b32 v5, v2, 48, v4 bitop3:0x48
	v_mov_b32_e32 v2, v220
	v_and_b32_e32 v0, 15, v4
	v_lshlrev_b32_e32 v2, 4, v2
	v_and_b32_e32 v2, 0xfffffc00, v2
	v_lshrrev_b32_e32 v1, 1, v4
	v_add_u32_e32 v3, 0x8000, v2
	v_and_or_b32 v0, v1, s57, v0
	v_readfirstlane_b32 s0, v3
	v_add_u32_e32 v3, 0x9000, v2
	v_lshl_or_b32 v128, v0, 6, v5
	v_lshl_add_u64 v[0:1], v[130:131], 0, s[18:19]
	s_mov_b32 m0, s0
	v_readfirstlane_b32 s0, v3
	v_add_u32_e32 v3, 0xa000, v2
	global_load_lds_dwordx4 v[0:1], off
	v_lshl_add_u64 v[0:1], v[132:133], 0, s[18:19]
	s_mov_b32 m0, s0
	v_readfirstlane_b32 s0, v3
	v_add_u32_e32 v2, 0xb000, v2
	global_load_lds_dwordx4 v[0:1], off
	v_lshl_add_u64 v[0:1], v[134:135], 0, s[18:19]
	s_mov_b32 m0, s0
	v_readfirstlane_b32 s0, v2
	global_load_lds_dwordx4 v[0:1], off
	v_lshl_add_u64 v[0:1], v[136:137], 0, s[18:19]
	s_mov_b32 m0, s0
	v_lshlrev_b32_e32 v4, 6, v4
	global_load_lds_dwordx4 v[0:1], off
	v_and_or_b32 v161, v4, s58, v5
	ds_read_b128 v[0:3], v128
	ds_read_b128 v[4:7], v161 offset:8192
	ds_read_b128 v[8:11], v128 offset:1024
	ds_read_b128 v[12:15], v161 offset:9216
	ds_read_b128 v[24:27], v161 offset:10240
	ds_read_b128 v[28:31], v161 offset:11264
	ds_read_b128 v[48:51], v128 offset:2048
	ds_read_b128 v[52:55], v128 offset:3072
	s_waitcnt vmcnt(4)
	v_mov_b32_e32 v70, v220
	s_waitcnt lgkmcnt(0)
	s_barrier
	v_lshl_add_u64 v[68:69], v[130:131], 0, s[20:21]
	v_lshlrev_b32_e32 v70, 4, v70
	v_and_b32_e32 v70, 0xfffffc00, v70
	v_add_u32_e32 v71, 0x1000, v70
	v_readfirstlane_b32 s0, v70
	s_mov_b32 m0, s0
	v_readfirstlane_b32 s0, v71
	v_add_u32_e32 v71, 0x2000, v70
	global_load_lds_dwordx4 v[68:69], off
	v_lshl_add_u64 v[68:69], v[132:133], 0, s[20:21]
	s_mov_b32 m0, s0
	v_readfirstlane_b32 s0, v71
	v_add_u32_e32 v70, 0x3000, v70
	global_load_lds_dwordx4 v[68:69], off
	v_lshl_add_u64 v[68:69], v[134:135], 0, s[20:21]
	s_mov_b32 m0, s0
	v_readfirstlane_b32 s0, v70
	global_load_lds_dwordx4 v[68:69], off
	v_lshl_add_u64 v[68:69], v[136:137], 0, s[20:21]
	s_mov_b32 m0, s0
	s_waitcnt lgkmcnt(0)
	v_mfma_f32_16x16x32_bf16 v[16:19], v[0:3], v[4:7], 0
	global_load_lds_dwordx4 v[68:69], off
	ds_read_b128 v[68:71], v128 offset:16384
	v_mfma_f32_16x16x32_bf16 v[20:23], v[0:3], v[12:15], 0
	v_mov_b32_e32 v88, v220
	v_mov_b32_e32 v94, v220
	v_lshl_add_u64 v[92:93], v[130:131], 0, s[28:29]
	v_mfma_f32_16x16x32_bf16 v[32:35], v[0:3], v[24:27], 0
	v_mov_b32_e32 v163, v220
	v_readlane_b32 s72, v228, 2
	v_readlane_b32 s76, v228, 6
	v_mfma_f32_16x16x32_bf16 v[0:3], v[0:3], v[28:31], 0
	v_readlane_b32 s77, v228, 7
	v_readlane_b32 s78, v228, 8
	v_readlane_b32 s79, v228, 9
	v_mfma_f32_16x16x32_bf16 v[36:39], v[8:11], v[4:7], 0
	s_mov_b32 s8, 0
	v_readlane_b32 s73, v228, 3
	v_readlane_b32 s74, v228, 4
	v_mfma_f32_16x16x32_bf16 v[40:43], v[8:11], v[12:15], 0
	v_readlane_b32 s75, v228, 5
	v_mfma_f32_16x16x32_bf16 v[44:47], v[8:11], v[24:27], 0
	v_mfma_f32_16x16x32_bf16 v[8:11], v[8:11], v[28:31], 0
	v_mfma_f32_16x16x32_bf16 v[56:59], v[48:51], v[4:7], 0
	v_mfma_f32_16x16x32_bf16 v[60:63], v[48:51], v[12:15], 0
	v_mfma_f32_16x16x32_bf16 v[64:67], v[48:51], v[24:27], 0
	v_mfma_f32_16x16x32_bf16 v[48:51], v[48:51], v[28:31], 0
	v_mfma_f32_16x16x32_bf16 v[4:7], v[52:55], v[4:7], 0
	v_mfma_f32_16x16x32_bf16 v[12:15], v[52:55], v[12:15], 0
	v_mfma_f32_16x16x32_bf16 v[24:27], v[52:55], v[24:27], 0
	v_mfma_f32_16x16x32_bf16 v[28:31], v[52:55], v[28:31], 0
	ds_read_b128 v[52:55], v161 offset:24576
	ds_read_b128 v[72:75], v128 offset:17408
	ds_read_b128 v[76:79], v161 offset:25600
	ds_read_b128 v[80:83], v161 offset:26624
	ds_read_b128 v[84:87], v161 offset:27648
	s_waitcnt lgkmcnt(0)
	v_mfma_f32_16x16x32_bf16 v[16:19], v[68:71], v[52:55], v[16:19]
	v_mfma_f32_16x16x32_bf16 v[20:23], v[68:71], v[76:79], v[20:23]
	v_mfma_f32_16x16x32_bf16 v[32:35], v[68:71], v[80:83], v[32:35]
	v_mfma_f32_16x16x32_bf16 v[0:3], v[68:71], v[84:87], v[0:3]
	v_mfma_f32_16x16x32_bf16 v[36:39], v[72:75], v[52:55], v[36:39]
	v_mfma_f32_16x16x32_bf16 v[40:43], v[72:75], v[76:79], v[40:43]
	v_mfma_f32_16x16x32_bf16 v[44:47], v[72:75], v[80:83], v[44:47]
	v_mfma_f32_16x16x32_bf16 v[8:11], v[72:75], v[84:87], v[8:11]
	ds_read_b128 v[68:71], v128 offset:18432
	ds_read_b128 v[72:75], v128 offset:19456
	s_waitcnt vmcnt(4)
	s_waitcnt lgkmcnt(0)
	s_waitcnt lgkmcnt(0)
	v_mfma_f32_16x16x32_bf16 v[56:59], v[68:71], v[52:55], v[56:59]
	s_barrier
	v_mfma_f32_16x16x32_bf16 v[4:7], v[72:75], v[52:55], v[4:7]
	v_mov_b32_e32 v54, v220
	v_lshl_add_u64 v[52:53], v[130:131], 0, s[22:23]
	v_lshlrev_b32_e32 v54, 4, v54
	v_and_b32_e32 v54, 0xfffffc00, v54
	v_add_u32_e32 v55, 0x4000, v54
	v_mfma_f32_16x16x32_bf16 v[60:63], v[68:71], v[76:79], v[60:63]
	v_readfirstlane_b32 s0, v55
	v_add_u32_e32 v55, 0x5000, v54
	s_mov_b32 m0, s0
	v_readfirstlane_b32 s0, v55
	v_add_u32_e32 v55, 0x6000, v54
	global_load_lds_dwordx4 v[52:53], off
	v_lshl_add_u64 v[52:53], v[132:133], 0, s[22:23]
	s_mov_b32 m0, s0
	v_readfirstlane_b32 s0, v55
	v_add_u32_e32 v54, 0x7000, v54
	global_load_lds_dwordx4 v[52:53], off
	v_lshl_add_u64 v[52:53], v[134:135], 0, s[22:23]
	s_mov_b32 m0, s0
	v_readfirstlane_b32 s0, v54
	global_load_lds_dwordx4 v[52:53], off
	v_lshl_add_u64 v[52:53], v[136:137], 0, s[22:23]
	s_mov_b32 m0, s0
	v_mfma_f32_16x16x32_bf16 v[64:67], v[68:71], v[80:83], v[64:67]
	global_load_lds_dwordx4 v[52:53], off
	ds_read_b128 v[52:55], v128 offset:32768
	v_mfma_f32_16x16x32_bf16 v[48:51], v[68:71], v[84:87], v[48:51]
	v_mfma_f32_16x16x32_bf16 v[12:15], v[72:75], v[76:79], v[12:15]
	v_mfma_f32_16x16x32_bf16 v[24:27], v[72:75], v[80:83], v[24:27]
	v_mfma_f32_16x16x32_bf16 v[28:31], v[72:75], v[84:87], v[28:31]
	ds_read_b128 v[68:71], v161 offset:40960
	ds_read_b128 v[72:75], v128 offset:33792
	ds_read_b128 v[76:79], v161 offset:41984
	ds_read_b128 v[80:83], v161 offset:43008
	ds_read_b128 v[84:87], v161 offset:44032
	s_waitcnt lgkmcnt(0)
	v_mfma_f32_16x16x32_bf16 v[16:19], v[52:55], v[68:71], v[16:19]
	v_mfma_f32_16x16x32_bf16 v[20:23], v[52:55], v[76:79], v[20:23]
	v_mfma_f32_16x16x32_bf16 v[32:35], v[52:55], v[80:83], v[32:35]
	v_mfma_f32_16x16x32_bf16 v[0:3], v[52:55], v[84:87], v[0:3]
	v_mfma_f32_16x16x32_bf16 v[36:39], v[72:75], v[68:71], v[36:39]
	v_mfma_f32_16x16x32_bf16 v[40:43], v[72:75], v[76:79], v[40:43]
	v_mfma_f32_16x16x32_bf16 v[44:47], v[72:75], v[80:83], v[44:47]
	v_mfma_f32_16x16x32_bf16 v[8:11], v[72:75], v[84:87], v[8:11]
	ds_read_b128 v[52:55], v128 offset:34816
	ds_read_b128 v[72:75], v128 offset:35840
	s_waitcnt vmcnt(4)
	s_waitcnt lgkmcnt(0)
	s_waitcnt lgkmcnt(0)
	v_mfma_f32_16x16x32_bf16 v[56:59], v[52:55], v[68:71], v[56:59]
	s_barrier
; __device__ __forceinline__ f32x4 mfma16(bf16x8 a, bf16x8 b, f32x4 c) { return __builtin_amdgcn_mfma_f32_16x16x32_bf16(a, b, c, 0, 0, 0); }
; #define GEMM_STEP(J, BUF, NBUF) do { asm volatile("s_waitcnt vmcnt(4)" ::: "memory"); RAW_BARRIER(); \
;     if ((J) + 2 < nk) gemm_issue(g, (J) + 2, NBUF, L); comp(BUF); } while (0)
; #define ZERO_ACC(acc) zero_acc(acc)
; __device__ __forceinline__ void gemm_main(f32x4 (&acc)[4][4], const GemmOps& g, int K, u16* lds) {
;     ...
;   auto comp = [&](int buf) __attribute__((always_inline)) {
;     const char* sb = L + buf * GEMM_STAGE_B;
;     bf16x8 a[4], b[4];
; #pragma unroll
;     for (int i = 0; i < 4; ++i) a[i] = *(const bf16x8*)(sb + offA[i]);
; #pragma unroll
;     for (int j = 0; j < 4; ++j) b[j] = *(const bf16x8*)(sb + offB[j]);
; #pragma unroll
;     for (int i = 0; i < 4; ++i)
; #pragma unroll
;       for (int j = 0; j < 4; ++j) acc[i][j] = mfma16(a[i], b[j], acc[i][j]);
;   };
;   const int nk = K >> 5;
;     ...
;   int j = 0;
;   for (; j + 3 <= nk - 1; j += 3) {
;     GEMM_STEP(j, 0, 2);
;     GEMM_STEP(j + 1, 1, 0);
;     GEMM_STEP(j + 2, 2, 1);
;   }
;   GEMM_STEP(j, 0, 2);
; __device__ void ph_gemm4(const P& p, u16* lds) {
;     ...
;   auto opsG = [&](int t) __attribute__((always_inline)) { return gemm_ops(p_Abf + (size_t)(t / NT) * 128 * DM, DM, p_WgT + (size_t)(t % NT) * 128 * DM, DM); };
;   GemmOps g = opsP(it);
;   __syncthreads();
;   gemm_prologue(g, lds);
;   while (true) {
;     const int mt = it / NT, nt = it % NT;
;     f32x4 acc[4][4]; ZERO_ACC(acc);
;     gemm_main(acc, g, 256, lds);
;     __syncthreads();
;     g = opsG(it);
	v_mfma_f32_16x16x32_bf16 v[60:63], v[52:55], v[76:79], v[60:63]
	v_mfma_f32_16x16x32_bf16 v[64:67], v[52:55], v[80:83], v[64:67]
	v_mfma_f32_16x16x32_bf16 v[48:51], v[52:55], v[84:87], v[48:51]
	v_lshlrev_b32_e32 v54, 4, v88
	v_and_b32_e32 v54, 0xfffffc00, v54
	v_add_u32_e32 v55, 0x8000, v54
	v_lshl_add_u64 v[52:53], v[130:131], 0, s[24:25]
	v_readfirstlane_b32 s0, v55
	v_add_u32_e32 v55, 0x9000, v54
	s_mov_b32 m0, s0
	v_readfirstlane_b32 s0, v55
	v_add_u32_e32 v55, 0xa000, v54
	global_load_lds_dwordx4 v[52:53], off
	v_lshl_add_u64 v[52:53], v[132:133], 0, s[24:25]
	s_mov_b32 m0, s0
	v_readfirstlane_b32 s0, v55
	v_add_u32_e32 v54, 0xb000, v54
	global_load_lds_dwordx4 v[52:53], off
	v_lshl_add_u64 v[52:53], v[134:135], 0, s[24:25]
	s_mov_b32 m0, s0
	v_readfirstlane_b32 s0, v54
	global_load_lds_dwordx4 v[52:53], off
	v_lshl_add_u64 v[52:53], v[136:137], 0, s[24:25]
	s_mov_b32 m0, s0
	v_mfma_f32_16x16x32_bf16 v[4:7], v[72:75], v[68:71], v[4:7]
	global_load_lds_dwordx4 v[52:53], off
	ds_read_b128 v[52:55], v128
	v_mfma_f32_16x16x32_bf16 v[12:15], v[72:75], v[76:79], v[12:15]
	v_mfma_f32_16x16x32_bf16 v[24:27], v[72:75], v[80:83], v[24:27]
	v_mfma_f32_16x16x32_bf16 v[28:31], v[72:75], v[84:87], v[28:31]
	ds_read_b128 v[68:71], v161 offset:8192
	ds_read_b128 v[72:75], v128 offset:1024
	ds_read_b128 v[76:79], v161 offset:9216
	ds_read_b128 v[80:83], v161 offset:10240
	ds_read_b128 v[84:87], v161 offset:11264
	s_waitcnt lgkmcnt(0)
	v_mfma_f32_16x16x32_bf16 v[16:19], v[52:55], v[68:71], v[16:19]
	v_mfma_f32_16x16x32_bf16 v[20:23], v[52:55], v[76:79], v[20:23]
	v_mfma_f32_16x16x32_bf16 v[32:35], v[52:55], v[80:83], v[32:35]
	v_mfma_f32_16x16x32_bf16 v[0:3], v[52:55], v[84:87], v[0:3]
	ds_read_b128 v[52:55], v128 offset:2048
	ds_read_b128 v[88:91], v128 offset:3072
	s_waitcnt vmcnt(4)
	s_waitcnt lgkmcnt(0)
	v_mfma_f32_16x16x32_bf16 v[36:39], v[72:75], v[68:71], v[36:39]
	s_barrier
	v_mfma_f32_16x16x32_bf16 v[40:43], v[72:75], v[76:79], v[40:43]
	v_mfma_f32_16x16x32_bf16 v[44:47], v[72:75], v[80:83], v[44:47]
	v_mfma_f32_16x16x32_bf16 v[8:11], v[72:75], v[84:87], v[8:11]
	v_mov_b32_e32 v74, v220
	v_lshl_add_u64 v[72:73], v[130:131], 0, s[26:27]
	v_lshlrev_b32_e32 v74, 4, v74
	v_and_b32_e32 v74, 0xfffffc00, v74
	s_waitcnt lgkmcnt(0)
	v_mfma_f32_16x16x32_bf16 v[56:59], v[52:55], v[68:71], v[56:59]
	v_readfirstlane_b32 s0, v74
	s_mov_b32 m0, s0
	v_mfma_f32_16x16x32_bf16 v[60:63], v[52:55], v[76:79], v[60:63]
	global_load_lds_dwordx4 v[72:73], off
	v_mfma_f32_16x16x32_bf16 v[64:67], v[52:55], v[80:83], v[64:67]
	v_mfma_f32_16x16x32_bf16 v[48:51], v[52:55], v[84:87], v[48:51]
	v_add_u32_e32 v54, 0x1000, v74
	v_lshl_add_u64 v[52:53], v[132:133], 0, s[26:27]
	v_readfirstlane_b32 s0, v54
	v_add_u32_e32 v54, 0x2000, v74
	s_mov_b32 m0, s0
	v_readfirstlane_b32 s0, v54
	v_add_u32_e32 v54, 0x3000, v74
	global_load_lds_dwordx4 v[52:53], off
	v_lshl_add_u64 v[52:53], v[134:135], 0, s[26:27]
	s_mov_b32 m0, s0
	v_readfirstlane_b32 s0, v54
	global_load_lds_dwordx4 v[52:53], off
	v_lshl_add_u64 v[52:53], v[136:137], 0, s[26:27]
	s_mov_b32 m0, s0
	v_mfma_f32_16x16x32_bf16 v[4:7], v[88:91], v[68:71], v[4:7]
	global_load_lds_dwordx4 v[52:53], off
	ds_read_b128 v[52:55], v128 offset:16384
	v_mfma_f32_16x16x32_bf16 v[12:15], v[88:91], v[76:79], v[12:15]
	ds_read_b128 v[68:71], v161 offset:24576
	ds_read_b128 v[72:75], v128 offset:17408
	ds_read_b128 v[76:79], v161 offset:25600
	v_mfma_f32_16x16x32_bf16 v[24:27], v[88:91], v[80:83], v[24:27]
	v_mfma_f32_16x16x32_bf16 v[28:31], v[88:91], v[84:87], v[28:31]
	ds_read_b128 v[80:83], v161 offset:26624
	ds_read_b128 v[84:87], v161 offset:27648
	s_waitcnt lgkmcnt(0)
	v_mfma_f32_16x16x32_bf16 v[16:19], v[52:55], v[68:71], v[16:19]
	v_mfma_f32_16x16x32_bf16 v[20:23], v[52:55], v[76:79], v[20:23]
	v_mfma_f32_16x16x32_bf16 v[32:35], v[52:55], v[80:83], v[32:35]
	v_mfma_f32_16x16x32_bf16 v[0:3], v[52:55], v[84:87], v[0:3]
	ds_read_b128 v[52:55], v128 offset:18432
	ds_read_b128 v[88:91], v128 offset:19456
	s_waitcnt vmcnt(4)
	s_waitcnt lgkmcnt(0)
	s_barrier
	v_mfma_f32_16x16x32_bf16 v[36:39], v[72:75], v[68:71], v[36:39]
	v_lshlrev_b32_e32 v94, 4, v94
	v_and_b32_e32 v94, 0xfffffc00, v94
	v_add_u32_e32 v95, 0x4000, v94
	v_mfma_f32_16x16x32_bf16 v[40:43], v[72:75], v[76:79], v[40:43]
	v_readfirstlane_b32 s0, v95
	s_mov_b32 m0, s0
	v_mfma_f32_16x16x32_bf16 v[44:47], v[72:75], v[80:83], v[44:47]
	global_load_lds_dwordx4 v[92:93], off
	v_mfma_f32_16x16x32_bf16 v[8:11], v[72:75], v[84:87], v[8:11]
	v_add_u32_e32 v74, 0x5000, v94
	v_lshl_add_u64 v[72:73], v[132:133], 0, s[28:29]
	v_readfirstlane_b32 s0, v74
	v_add_u32_e32 v74, 0x6000, v94
	s_waitcnt lgkmcnt(0)
	v_mfma_f32_16x16x32_bf16 v[56:59], v[52:55], v[68:71], v[56:59]
	s_mov_b32 m0, s0
	v_readfirstlane_b32 s0, v74
	global_load_lds_dwordx4 v[72:73], off
	v_mfma_f32_16x16x32_bf16 v[60:63], v[52:55], v[76:79], v[60:63]
	v_lshl_add_u64 v[72:73], v[134:135], 0, s[28:29]
	s_mov_b32 m0, s0
	v_mfma_f32_16x16x32_bf16 v[64:67], v[52:55], v[80:83], v[64:67]
	global_load_lds_dwordx4 v[72:73], off
	v_mfma_f32_16x16x32_bf16 v[48:51], v[52:55], v[84:87], v[48:51]
	v_add_u32_e32 v54, 0x7000, v94
	v_lshl_add_u64 v[52:53], v[136:137], 0, s[28:29]
	v_readfirstlane_b32 s0, v54
	s_mov_b32 m0, s0
	v_mfma_f32_16x16x32_bf16 v[4:7], v[88:91], v[68:71], v[4:7]
	global_load_lds_dwordx4 v[52:53], off
	ds_read_b128 v[52:55], v128 offset:32768
	v_mfma_f32_16x16x32_bf16 v[12:15], v[88:91], v[76:79], v[12:15]
	ds_read_b128 v[68:71], v161 offset:40960
	ds_read_b128 v[72:75], v128 offset:33792
	ds_read_b128 v[76:79], v161 offset:41984
	s_and_b32 s81, s69, 7
	s_lshr_b32 s82, s69, 3
	s_lshr_b32 s83, s82, 6
	s_and_b32 s84, s82, 63
	s_cmp_lt_u32 s83, 4
	s_cselect_b32 s85, 3, 0
	s_cselect_b32 s86, 7, 0
	s_lshr_b32 s87, s84, s85
	s_and_b32 s84, s84, s86
	s_lshl_b32 s83, s83, 3
	s_add_u32 s83, s83, s84
	s_mul_i32 s81, s81, 33
	s_add_u32 s81, s81, s83
	s_mul_i32 s81, s81, 8
	s_add_u32 s80, s81, s87
	s_ashr_i32 s0, s80, 31
	s_lshr_b32 s0, s0, 29
	v_mfma_f32_16x16x32_bf16 v[24:27], v[88:91], v[80:83], v[24:27]
	s_add_i32 s1, s80, s0
	s_ashr_i32 s0, s1, 3
	s_and_b32 s1, s1, -8
	v_mfma_f32_16x16x32_bf16 v[28:31], v[88:91], v[84:87], v[28:31]
	ds_read_b128 v[80:83], v161 offset:43008
	ds_read_b128 v[84:87], v161 offset:44032
	s_sub_i32 s50, s80, s1
	s_ashr_i32 s1, s0, 31
	s_waitcnt lgkmcnt(0)
	v_mfma_f32_16x16x32_bf16 v[16:19], v[52:55], v[68:71], v[16:19]
	s_lshl_b64 s[4:5], s[0:1], 18
	s_add_u32 s10, s53, s4
	s_addc_u32 s11, s54, s5
	v_mfma_f32_16x16x32_bf16 v[20:23], v[52:55], v[76:79], v[20:23]
	s_ashr_i32 s51, s50, 31
	s_lshl_b64 s[6:7], s[50:51], 18
	s_add_u32 s12, s55, s6
	v_mfma_f32_16x16x32_bf16 v[32:35], v[52:55], v[80:83], v[32:35]
	s_addc_u32 s13, s56, s7
	s_mov_b64 s[88:89], s[10:11]
	s_mov_b64 s[90:91], s[12:13]
	v_mfma_f32_16x16x32_bf16 v[0:3], v[52:55], v[84:87], v[0:3]
	ds_read_b128 v[52:55], v128 offset:34816
	ds_read_b128 v[88:91], v128 offset:35840
	s_waitcnt vmcnt(4)
	s_waitcnt lgkmcnt(0)
	v_mfma_f32_16x16x32_bf16 v[36:39], v[72:75], v[68:71], v[36:39]
	s_barrier
; __device__ __forceinline__ int tid_() { int t = threadIdx.x; asm volatile("" : "+v"(t)); return t; }
; #define ZERO_ACC(acc) zero_acc(acc)
; __device__ __forceinline__ void gemm_issue(const GemmOps& g, int kt, int buf, char* L) {
;   const int wid = tid_() >> 6;
;   char* sb = L + buf * GEMM_STAGE_B;
;   __builtin_amdgcn_global_load_lds((const unsigned*)(g.a0 + kt * 32), (unsigned*)(sb + wid * 1024), 16, 0, 0);
;   __builtin_amdgcn_global_load_lds((const unsigned*)(g.a1 + kt * 32), (unsigned*)(sb + (wid + 4) * 1024), 16, 0, 0);
;   __builtin_amdgcn_global_load_lds((const unsigned*)(g.b0 + kt * 32), (unsigned*)(sb + 8192 + wid * 1024), 16, 0, 0);
;   __builtin_amdgcn_global_load_lds((const unsigned*)(g.b1 + kt * 32), (unsigned*)(sb + 8192 + (wid + 4) * 1024), 16, 0, 0);
; }
; __device__ __forceinline__ void gemm_prologue(const GemmOps& g, u16* lds) {
;   gemm_issue(g, 0, 0, (char*)lds); gemm_issue(g, 1, 1, (char*)lds);
; }
; __device__ void ph_gemm4(const P& p, u16* lds) {
;     ...
;   auto opsG = [&](int t) __attribute__((always_inline)) { return gemm_ops(p_Abf + (size_t)(t / NT) * 128 * DM, DM, p_WgT + (size_t)(t % NT) * 128 * DM, DM); };
;   GemmOps g = opsP(it);
;   __syncthreads();
;   gemm_prologue(g, lds);
;   while (true) {
;     const int mt = it / NT, nt = it % NT;
;     f32x4 acc[4][4]; ZERO_ACC(acc);
;     gemm_main(acc, g, 256, lds);
;     __syncthreads();
;     g = opsG(it);
;     gemm_prologue(g, lds);
	v_mfma_f32_16x16x32_bf16 v[40:43], v[72:75], v[76:79], v[40:43]
	v_mfma_f32_16x16x32_bf16 v[44:47], v[72:75], v[80:83], v[44:47]
	v_mfma_f32_16x16x32_bf16 v[8:11], v[72:75], v[84:87], v[8:11]
	ds_read_b128 v[72:75], v161 offset:11264
	ds_read_b128 v[92:95], v161 offset:10240
	ds_read_b128 v[96:99], v161 offset:9216
	ds_read_b128 v[100:103], v161 offset:8192
	ds_read_b128 v[104:107], v128 offset:3072
	ds_read_b128 v[108:111], v128 offset:2048
	ds_read_b128 v[112:115], v128 offset:1024
	ds_read_b128 v[116:119], v128
	s_waitcnt lgkmcnt(0)
	v_mfma_f32_16x16x32_bf16 v[56:59], v[52:55], v[68:71], v[56:59]
	s_waitcnt vmcnt(0)
	s_waitcnt lgkmcnt(0)
	s_barrier
	v_mfma_f32_16x16x32_bf16 v[60:63], v[52:55], v[76:79], v[60:63]
	ds_read_b128 v[120:123], v128 offset:16384
	ds_read_b128 v[124:127], v128 offset:17408
	ds_read_b128 v[138:141], v128 offset:18432
	ds_read_b128 v[164:167], v128 offset:19456
	ds_read_b128 v[142:145], v161 offset:24576
	ds_read_b128 v[168:171], v161 offset:25600
	ds_read_b128 v[172:175], v161 offset:26624
	ds_read_b128 v[176:179], v161 offset:27648
	v_mfma_f32_16x16x32_bf16 v[64:67], v[52:55], v[80:83], v[64:67]
	s_waitcnt vmcnt(0) lgkmcnt(0)
	s_barrier
	v_mfma_f32_16x16x32_bf16 v[48:51], v[52:55], v[84:87], v[48:51]
	v_mov_b32_e32 v52, v220
	v_mfma_f32_16x16x32_bf16 v[16:19], v[116:119], v[100:103], v[16:19]
	v_lshrrev_b32_e32 v53, 2, v163
	v_ashrrev_i32_e32 v52, 2, v52
	v_lshrrev_b32_e32 v180, 4, v163
	v_bfi_b32 v52, -16, v52, v53
	v_xor_b32_e32 v55, v180, v163
	v_add_u32_e32 v54, 64, v52
	v_ashrrev_i32_e32 v53, 31, v52
	v_lshlrev_b32_e32 v55, 4, v55
	v_mfma_f32_16x16x32_bf16 v[20:23], v[116:119], v[96:99], v[20:23]
	v_and_b32_e32 v128, 48, v55
	v_ashrrev_i32_e32 v55, 31, v54
	v_mfma_f32_16x16x32_bf16 v[32:35], v[116:119], v[92:95], v[32:35]
	v_mfma_f32_16x16x32_bf16 v[0:3], v[116:119], v[72:75], v[0:3]
	v_lshlrev_b64 v[116:117], 11, v[52:53]
	v_lshl_add_u64 v[52:53], s[10:11], 0, v[116:117]
	v_lshlrev_b64 v[118:119], 11, v[54:55]
	v_lshl_add_u64 v[130:131], v[52:53], 0, v[128:129]
	v_lshl_add_u64 v[52:53], s[10:11], 0, v[118:119]
	v_lshl_add_u64 v[132:133], v[52:53], 0, v[128:129]
	v_lshl_add_u64 v[52:53], s[12:13], 0, v[116:117]
	v_lshl_add_u64 v[134:135], v[52:53], 0, v[128:129]
	v_lshl_add_u64 v[52:53], s[12:13], 0, v[118:119]
	v_lshl_add_u64 v[136:137], v[52:53], 0, v[128:129]
	v_mov_b32_e32 v52, v220
	v_mfma_f32_16x16x32_bf16 v[12:15], v[88:91], v[76:79], v[12:15]
	v_lshlrev_b32_e32 v52, 4, v52
	v_and_b32_e32 v52, 0xfffffc00, v52
	v_add_u32_e32 v53, 0x1000, v52
	v_readfirstlane_b32 s1, v52
	s_mov_b32 m0, s1
	v_readfirstlane_b32 s1, v53
	v_add_u32_e32 v53, 0x2000, v52
	s_mov_b32 m0, s92
	s_nop 0
	global_load_lds_dwordx4 v206, s[88:89]
	s_add_u32 m0, m0, 0x1000
	s_nop 0
	global_load_lds_dwordx4 v207, s[88:89]
	s_add_u32 m0, m0, 0x1000
	s_nop 0
	global_load_lds_dwordx4 v208, s[88:89]
	s_add_u32 m0, m0, 0x1000
	s_nop 0
	global_load_lds_dwordx4 v209, s[88:89]
	s_add_u32 m0, m0, 0x1000
	s_nop 0
	global_load_lds_dwordx4 v206, s[90:91]
	s_add_u32 m0, m0, 0x1000
	s_nop 0
	global_load_lds_dwordx4 v207, s[90:91]
	s_add_u32 m0, m0, 0x1000
	s_nop 0
	global_load_lds_dwordx4 v208, s[90:91]
	s_add_u32 m0, m0, 0x1000
	s_nop 0
	global_load_lds_dwordx4 v209, s[90:91]
	s_mov_b32 m0, s1
	v_readfirstlane_b32 s1, v53
	v_add_u32_e32 v52, 0x3000, v52
	v_mfma_f32_16x16x32_bf16 v[28:31], v[88:91], v[84:87], v[28:31]
	s_mov_b32 m0, s1
	v_readfirstlane_b32 s1, v52
	s_mov_b32 m0, s1
	v_mov_b32_e32 v52, v220
	v_mfma_f32_16x16x32_bf16 v[4:7], v[88:91], v[68:71], v[4:7]
	v_lshlrev_b32_e32 v52, 4, v52
	s_mov_b64 s[12:13], s[76:77]
	s_mov_b64 s[14:15], s[78:79]
	v_mfma_f32_16x16x32_bf16 v[24:27], v[88:91], v[80:83], v[24:27]
	s_add_u32 s6, s14, s6
	s_addc_u32 s7, s15, s7
	s_add_u32 s4, s14, s4
	v_mfma_f32_16x16x32_bf16 v[40:43], v[112:115], v[96:99], v[40:43]
	s_addc_u32 s5, s15, s5
	v_mfma_f32_16x16x32_bf16 v[88:91], v[108:111], v[96:99], v[60:63]
	v_mfma_f32_16x16x32_bf16 v[12:15], v[104:107], v[96:99], v[12:15]
	v_mfma_f32_16x16x32_bf16 v[96:99], v[104:107], v[72:75], v[28:31]
	s_nop 2
	v_and_b32_e32 v28, 0xfffffc00, v52
	v_add_u32_e32 v29, 0x4000, v28
	v_mfma_f32_16x16x32_bf16 v[52:55], v[120:123], v[142:145], v[16:19]
	v_readfirstlane_b32 s1, v29
	s_mov_b32 m0, s1
	v_mov_b32_e32 v29, v129
	v_add_u32_e32 v18, 0x5000, v28
	v_mfma_f32_16x16x32_bf16 v[36:39], v[112:115], v[100:103], v[36:39]
	v_readfirstlane_b32 s1, v18
	v_lshl_add_u64 v[16:17], v[132:133], 0, 64
	v_mov_b32_e32 v30, v129
	v_mfma_f32_16x16x32_bf16 v[44:47], v[112:115], v[92:95], v[44:47]
	v_mov_b32_e32 v31, v129
	v_mov_b32_e32 v18, v129
	v_mov_b32_e32 v19, v129
	v_mfma_f32_16x16x32_bf16 v[8:11], v[112:115], v[72:75], v[8:11]
	v_mfma_f32_16x16x32_bf16 v[84:87], v[108:111], v[100:103], v[56:59]
	v_mfma_f32_16x16x32_bf16 v[112:115], v[108:111], v[92:95], v[64:67]
	s_nop 1
	v_lshl_add_u64 v[56:57], v[130:131], 0, 64
	v_mfma_f32_16x16x32_bf16 v[64:67], v[120:123], v[176:179], v[0:3]
	s_mov_b32 m0, s1
	s_nop 0
	v_add_u32_e32 v2, 0x6000, v28
	v_lshl_add_u64 v[0:1], v[134:135], 0, 64
	v_readfirstlane_b32 s1, v2
	v_add_u32_e32 v2, 0x7000, v28
	s_mov_b32 m0, s1
	v_readfirstlane_b32 s1, v2
	v_lshl_add_u64 v[0:1], v[136:137], 0, 64
	s_mov_b32 m0, s1
	v_mfma_f32_16x16x32_bf16 v[48:51], v[108:111], v[72:75], v[48:51]
	v_mov_b32_e32 v0, v220
	v_mfma_f32_16x16x32_bf16 v[4:7], v[104:107], v[100:103], v[4:7]
	v_mov_b32_e32 v28, v129
	v_lshlrev_b32_e32 v3, 2, v0
	v_mfma_f32_16x16x32_bf16 v[24:27], v[104:107], v[92:95], v[24:27]
	v_and_b32_e32 v1, 15, v0
	v_lshrrev_b32_e32 v2, 1, v0
	v_bitop3_b32 v3, v3, 48, v0 bitop3:0x48
	v_mfma_f32_16x16x32_bf16 v[56:59], v[120:123], v[168:171], v[20:23]
; __device__ __forceinline__ f32x4 mfma16(bf16x8 a, bf16x8 b, f32x4 c) { return __builtin_amdgcn_mfma_f32_16x16x32_bf16(a, b, c, 0, 0, 0); }
; #define ZERO_ACC(acc) zero_acc(acc)
; __device__ __forceinline__ void gemm_main(f32x4 (&acc)[4][4], const GemmOps& g, int K, u16* lds) {
;     ...
; #pragma unroll
;     for (int i = 0; i < 4; ++i)
; #pragma unroll
;       for (int j = 0; j < 4; ++j) acc[i][j] = mfma16(a[i], b[j], acc[i][j]);
; __device__ void ph_gemm4(const P& p, u16* lds) {
;     ...
;     ZERO_ACC(acc);
;     gemm_main(acc, g, DM, lds);
	v_lshlrev_b32_e32 v0, 6, v0
	v_and_or_b32 v1, v2, s57, v1
	v_and_or_b32 v162, v0, s58, v3
	v_mfma_f32_16x16x32_bf16 v[60:63], v[120:123], v[172:175], v[32:35]
	v_bitop3_b32 v0, v180, 3, v163 bitop3:0x48
	v_lshl_or_b32 v161, v1, 6, v3
	v_lshlrev_b32_e32 v128, 4, v0
	v_mfma_f32_16x16x32_bf16 v[68:71], v[124:127], v[142:145], v[36:39]
	v_mov_b32_e32 v0, v129
	v_mov_b32_e32 v1, v129
	v_mov_b32_e32 v2, v129
	v_mfma_f32_16x16x32_bf16 v[72:75], v[124:127], v[168:171], v[40:43]
	v_mov_b32_e32 v3, v129
	v_mov_b32_e32 v16, v129
	v_mov_b32_e32 v17, v129
	v_mfma_f32_16x16x32_bf16 v[76:79], v[124:127], v[172:175], v[44:47]
	v_mov_b32_e32 v20, v129
	v_mov_b32_e32 v21, v129
	v_mov_b32_e32 v22, v129
	v_mfma_f32_16x16x32_bf16 v[80:83], v[124:127], v[176:179], v[8:11]
	v_mov_b32_e32 v23, v129
	v_mov_b32_e32 v32, v129
	v_mov_b32_e32 v33, v129
	v_mfma_f32_16x16x32_bf16 v[84:87], v[138:141], v[142:145], v[84:87]
	v_mov_b32_e32 v8, v129
	v_mov_b32_e32 v9, v129
	v_mov_b32_e32 v10, v129
	v_mfma_f32_16x16x32_bf16 v[88:91], v[138:141], v[168:171], v[88:91]
	v_mov_b32_e32 v11, v129
	v_mov_b32_e32 v34, v129
	v_mov_b32_e32 v35, v129
	v_mfma_f32_16x16x32_bf16 v[92:95], v[138:141], v[172:175], v[112:115]
	v_mov_b32_e32 v36, v129
	v_mov_b32_e32 v37, v129
	v_mov_b32_e32 v38, v129
	v_mfma_f32_16x16x32_bf16 v[100:103], v[138:141], v[176:179], v[48:51]
	v_lshl_add_u64 v[138:139], s[6:7], 0, v[118:119]
	v_lshl_add_u64 v[140:141], s[6:7], 0, v[116:117]
	v_mov_b32_e32 v39, v129
	v_mfma_f32_16x16x32_bf16 v[104:107], v[164:167], v[142:145], v[4:7]
	v_lshl_add_u64 v[142:143], s[4:5], 0, v[118:119]
	v_lshl_add_u64 v[144:145], s[4:5], 0, v[116:117]
	v_mov_b32_e32 v40, v129
	v_mfma_f32_16x16x32_bf16 v[108:111], v[164:167], v[168:171], v[12:15]
	v_mov_b32_e32 v4, v129
	v_mov_b32_e32 v5, v129
	v_mov_b32_e32 v6, v129
	v_mfma_f32_16x16x32_bf16 v[112:115], v[164:167], v[172:175], v[24:27]
	v_mov_b32_e32 v7, v129
	v_mov_b32_e32 v12, v129
	v_mov_b32_e32 v13, v129
	v_mfma_f32_16x16x32_bf16 v[96:99], v[164:167], v[176:179], v[96:99]
	v_mov_b32_e32 v14, v129
	v_mov_b32_e32 v15, v129
	v_mov_b32_e32 v24, v129
	v_mov_b32_e32 v25, v129
	v_mov_b32_e32 v26, v129
	v_mov_b32_e32 v27, v129
	v_mov_b32_e32 v41, v129
	v_mov_b32_e32 v42, v129
	v_mov_b32_e32 v43, v129
	v_mov_b32_e32 v44, v129
	v_mov_b32_e32 v45, v129
	v_mov_b32_e32 v46, v129
	v_mov_b32_e32 v47, v129
	v_mov_b32_e32 v48, v129
	v_mov_b32_e32 v49, v129
	v_mov_b32_e32 v50, v129
	v_mov_b32_e32 v51, v129
	v_mov_b32_e32 v116, v129
	v_mov_b32_e32 v117, v129
	v_mov_b32_e32 v118, v129
	v_mov_b32_e32 v119, v129
	v_mov_b32_e32 v120, v129
	v_mov_b32_e32 v121, v129
	v_mov_b32_e32 v122, v129
	v_mov_b32_e32 v123, v129
	v_mov_b32_e32 v124, v129
	v_mov_b32_e32 v125, v129
	v_mov_b32_e32 v126, v129
	v_mov_b32_e32 v127, v129
.LBB0_1114:
	v_mov_b32_e32 v124, 0
	v_mov_b32_e32 v125, 0
	v_mov_b32_e32 v126, 0
	v_mov_b32_e32 v127, 0
	v_mov_b32_e32 v120, 0
	v_mov_b32_e32 v121, 0
	v_mov_b32_e32 v122, 0
	v_mov_b32_e32 v123, 0
	v_mov_b32_e32 v116, 0
	v_mov_b32_e32 v117, 0
	v_mov_b32_e32 v118, 0
	v_mov_b32_e32 v119, 0
	v_mov_b32_e32 v48, 0
	v_mov_b32_e32 v49, 0
	v_mov_b32_e32 v50, 0
	v_mov_b32_e32 v51, 0
	v_mov_b32_e32 v44, 0
	v_mov_b32_e32 v45, 0
	v_mov_b32_e32 v46, 0
	v_mov_b32_e32 v47, 0
	v_mov_b32_e32 v40, 0
	v_mov_b32_e32 v41, 0
	v_mov_b32_e32 v42, 0
	v_mov_b32_e32 v43, 0
	v_mov_b32_e32 v36, 0
	v_mov_b32_e32 v37, 0
	v_mov_b32_e32 v38, 0
	v_mov_b32_e32 v39, 0
	v_mov_b32_e32 v32, 0
	v_mov_b32_e32 v33, 0
	v_mov_b32_e32 v34, 0
	v_mov_b32_e32 v35, 0
	v_mov_b32_e32 v28, 0
	v_mov_b32_e32 v29, 0
	v_mov_b32_e32 v30, 0
	v_mov_b32_e32 v31, 0
	v_mov_b32_e32 v24, 0
	v_mov_b32_e32 v25, 0
	v_mov_b32_e32 v26, 0
	v_mov_b32_e32 v27, 0
	v_mov_b32_e32 v20, 0
	v_mov_b32_e32 v21, 0
	v_mov_b32_e32 v22, 0
	v_mov_b32_e32 v23, 0
	v_mov_b32_e32 v16, 0
	v_mov_b32_e32 v17, 0
	v_mov_b32_e32 v18, 0
	v_mov_b32_e32 v19, 0
	v_mov_b32_e32 v12, 0
	v_mov_b32_e32 v13, 0
	v_mov_b32_e32 v14, 0
	v_mov_b32_e32 v15, 0
	v_mov_b32_e32 v8, 0
	v_mov_b32_e32 v9, 0
	v_mov_b32_e32 v10, 0
	v_mov_b32_e32 v11, 0
	v_mov_b32_e32 v4, 0
	v_mov_b32_e32 v5, 0
	v_mov_b32_e32 v6, 0
	v_mov_b32_e32 v7, 0
	v_mov_b32_e32 v0, 0
	v_mov_b32_e32 v1, 0
	v_mov_b32_e32 v2, 0
	v_mov_b32_e32 v3, 0
	s_mov_b32 s94, 7
.Lg4_k:
	s_waitcnt vmcnt(0)
	s_barrier
; __device__ __forceinline__ int tid_() { int t = threadIdx.x; asm volatile("" : "+v"(t)); return t; }
; __device__ __forceinline__ f32x4 mfma16(bf16x8 a, bf16x8 b, f32x4 c) { return __builtin_amdgcn_mfma_f32_16x16x32_bf16(a, b, c, 0, 0, 0); }
; #define RAW_BARRIER() do { asm volatile("s_waitcnt lgkmcnt(0)" ::: "memory"); __builtin_amdgcn_s_barrier(); } while (0)
; #define GEMM_STEP(J, BUF, NBUF) do { asm volatile("s_waitcnt vmcnt(4)" ::: "memory"); RAW_BARRIER(); \
;     if ((J) + 2 < nk) gemm_issue(g, (J) + 2, NBUF, L); comp(BUF); } while (0)
; __device__ __forceinline__ void gemm_main(f32x4 (&acc)[4][4], const GemmOps& g, int K, u16* lds) {
;   const int tid = tid_(), lane = tid & 63, wid = tid >> 6;
;   const int wm = wid >> 1, wn = wid & 1, fr = lane & 15, fq = lane >> 4;
;   char* L = (char*)lds;
;   int offA[4], offB[4];
; #pragma unroll
;   for (int i = 0; i < 4; ++i) {
;     const int Ra = wm * 64 + i * 16 + fr, Rb = wn * 64 + i * 16 + fr;
;     offA[i] = Ra * 64 + ((fq ^ ((Ra >> 2) & 3)) << 4);
;     offB[i] = 8192 + Rb * 64 + ((fq ^ ((Rb >> 2) & 3)) << 4);
;   }
;   auto comp = [&](int buf) __attribute__((always_inline)) {
;     const char* sb = L + buf * GEMM_STAGE_B;
;     bf16x8 a[4], b[4];
; #pragma unroll
;     for (int i = 0; i < 4; ++i) a[i] = *(const bf16x8*)(sb + offA[i]);
; #pragma unroll
;     for (int j = 0; j < 4; ++j) b[j] = *(const bf16x8*)(sb + offB[j]);
; #pragma unroll
;     for (int i = 0; i < 4; ++i)
; #pragma unroll
;       for (int j = 0; j < 4; ++j) acc[i][j] = mfma16(a[i], b[j], acc[i][j]);
;   };
;   const int nk = K >> 5;
;     ...
;   int j = 0;
;   for (; j + 3 <= nk - 1; j += 3) {
;     GEMM_STEP(j, 0, 2);
;     GEMM_STEP(j + 1, 1, 0);
;     GEMM_STEP(j + 2, 2, 1);
;   }
;   GEMM_STEP(j, 0, 2);
;   asm volatile("s_waitcnt vmcnt(0)" ::: "memory");
;   RAW_BARRIER();
;   comp(1);
	s_add_u32 s88, s88, 0x80
	s_addc_u32 s89, s89, 0
	s_add_u32 s90, s90, 0x80
	s_addc_u32 s91, s91, 0
	s_mov_b32 m0, s93
	ds_read_b128 v[164:167], v210 offset:0
	global_load_lds_dwordx4 v206, s[88:89]
	s_add_u32 m0, m0, 0x1000
	ds_read_b128 v[168:171], v210 offset:2048
	global_load_lds_dwordx4 v207, s[88:89]
	s_add_u32 m0, m0, 0x1000
	ds_read_b128 v[172:175], v210 offset:4096
	global_load_lds_dwordx4 v208, s[88:89]
	s_add_u32 m0, m0, 0x1000
	ds_read_b128 v[176:179], v210 offset:6144
	global_load_lds_dwordx4 v209, s[88:89]
	s_add_u32 m0, m0, 0x1000
	ds_read_b128 v[180:183], v212 offset:0
	global_load_lds_dwordx4 v206, s[90:91]
	s_add_u32 m0, m0, 0x1000
	ds_read_b128 v[184:187], v212 offset:2048
	global_load_lds_dwordx4 v207, s[90:91]
	s_add_u32 m0, m0, 0x1400
	ds_read_b128 v[188:191], v212 offset:4096
	global_load_lds_dwordx4 v208, s[90:91]
	s_add_u32 m0, m0, 0x1000
	ds_read_b128 v[192:195], v212 offset:6144
	global_load_lds_dwordx4 v209, s[90:91]
	ds_read_b128 v[196:199], v211 offset:0
	ds_read_b128 v[200:203], v211 offset:2048
	ds_read_b128 v[138:141], v211 offset:4096
	ds_read_b128 v[142:145], v211 offset:6144
	s_waitcnt lgkmcnt(4)
	v_mfma_f32_16x16x32_bf16 v[124:127], v[164:167], v[180:183], v[124:127]
	v_mfma_f32_16x16x32_bf16 v[120:123], v[164:167], v[184:187], v[120:123]
	v_mfma_f32_16x16x32_bf16 v[116:119], v[164:167], v[188:191], v[116:119]
	v_mfma_f32_16x16x32_bf16 v[48:51], v[164:167], v[192:195], v[48:51]
	v_mfma_f32_16x16x32_bf16 v[44:47], v[168:171], v[180:183], v[44:47]
	v_mfma_f32_16x16x32_bf16 v[40:43], v[168:171], v[184:187], v[40:43]
	v_mfma_f32_16x16x32_bf16 v[36:39], v[168:171], v[188:191], v[36:39]
	v_mfma_f32_16x16x32_bf16 v[32:35], v[168:171], v[192:195], v[32:35]
	v_mfma_f32_16x16x32_bf16 v[28:31], v[172:175], v[180:183], v[28:31]
	v_mfma_f32_16x16x32_bf16 v[24:27], v[172:175], v[184:187], v[24:27]
	v_mfma_f32_16x16x32_bf16 v[20:23], v[172:175], v[188:191], v[20:23]
	v_mfma_f32_16x16x32_bf16 v[16:19], v[172:175], v[192:195], v[16:19]
	v_mfma_f32_16x16x32_bf16 v[12:15], v[176:179], v[180:183], v[12:15]
	v_mfma_f32_16x16x32_bf16 v[8:11], v[176:179], v[184:187], v[8:11]
	v_mfma_f32_16x16x32_bf16 v[4:7], v[176:179], v[188:191], v[4:7]
	v_mfma_f32_16x16x32_bf16 v[0:3], v[176:179], v[192:195], v[0:3]
	ds_read_b128 v[180:183], v213 offset:0
	ds_read_b128 v[184:187], v213 offset:2048
	ds_read_b128 v[188:191], v213 offset:4096
	ds_read_b128 v[192:195], v213 offset:6144
	s_waitcnt lgkmcnt(0)
	v_mfma_f32_16x16x32_bf16 v[124:127], v[196:199], v[180:183], v[124:127]
	v_mfma_f32_16x16x32_bf16 v[120:123], v[196:199], v[184:187], v[120:123]
	v_mfma_f32_16x16x32_bf16 v[116:119], v[196:199], v[188:191], v[116:119]
	v_mfma_f32_16x16x32_bf16 v[48:51], v[196:199], v[192:195], v[48:51]
	v_mfma_f32_16x16x32_bf16 v[44:47], v[200:203], v[180:183], v[44:47]
	v_mfma_f32_16x16x32_bf16 v[40:43], v[200:203], v[184:187], v[40:43]
	v_mfma_f32_16x16x32_bf16 v[36:39], v[200:203], v[188:191], v[36:39]
	v_mfma_f32_16x16x32_bf16 v[32:35], v[200:203], v[192:195], v[32:35]
	v_mfma_f32_16x16x32_bf16 v[28:31], v[138:141], v[180:183], v[28:31]
	v_mfma_f32_16x16x32_bf16 v[24:27], v[138:141], v[184:187], v[24:27]
	v_mfma_f32_16x16x32_bf16 v[20:23], v[138:141], v[188:191], v[20:23]
	v_mfma_f32_16x16x32_bf16 v[16:19], v[138:141], v[192:195], v[16:19]
	v_mfma_f32_16x16x32_bf16 v[12:15], v[142:145], v[180:183], v[12:15]
	v_mfma_f32_16x16x32_bf16 v[8:11], v[142:145], v[184:187], v[8:11]
	v_mfma_f32_16x16x32_bf16 v[4:7], v[142:145], v[188:191], v[4:7]
	v_mfma_f32_16x16x32_bf16 v[0:3], v[142:145], v[192:195], v[0:3]
	s_waitcnt vmcnt(0)
	s_barrier
	s_add_u32 s88, s88, 0x80
	s_addc_u32 s89, s89, 0
	s_add_u32 s90, s90, 0x80
	s_addc_u32 s91, s91, 0
	s_mov_b32 m0, s92
	ds_read_b128 v[164:167], v210 offset:32768
	global_load_lds_dwordx4 v206, s[88:89]
	s_add_u32 m0, m0, 0x1000
	ds_read_b128 v[168:171], v210 offset:34816
	global_load_lds_dwordx4 v207, s[88:89]
	s_add_u32 m0, m0, 0x1000
	ds_read_b128 v[172:175], v210 offset:36864
	global_load_lds_dwordx4 v208, s[88:89]
	s_add_u32 m0, m0, 0x1000
	ds_read_b128 v[176:179], v210 offset:38912
	global_load_lds_dwordx4 v209, s[88:89]
	s_add_u32 m0, m0, 0x1000
	ds_read_b128 v[180:183], v214 offset:32768
	global_load_lds_dwordx4 v206, s[90:91]
	s_add_u32 m0, m0, 0x1000
	ds_read_b128 v[184:187], v214 offset:34816
	global_load_lds_dwordx4 v207, s[90:91]
	s_add_u32 m0, m0, 0x1000
	ds_read_b128 v[188:191], v214 offset:36864
	global_load_lds_dwordx4 v208, s[90:91]
	s_add_u32 m0, m0, 0x1000
	ds_read_b128 v[192:195], v214 offset:38912
	global_load_lds_dwordx4 v209, s[90:91]
	ds_read_b128 v[196:199], v211 offset:32768
	ds_read_b128 v[200:203], v211 offset:34816
	ds_read_b128 v[138:141], v211 offset:36864
	ds_read_b128 v[142:145], v211 offset:38912
	s_waitcnt lgkmcnt(4)
	v_mfma_f32_16x16x32_bf16 v[124:127], v[164:167], v[180:183], v[124:127]
	v_mfma_f32_16x16x32_bf16 v[120:123], v[164:167], v[184:187], v[120:123]
	v_mfma_f32_16x16x32_bf16 v[116:119], v[164:167], v[188:191], v[116:119]
	v_mfma_f32_16x16x32_bf16 v[48:51], v[164:167], v[192:195], v[48:51]
	v_mfma_f32_16x16x32_bf16 v[44:47], v[168:171], v[180:183], v[44:47]
	v_mfma_f32_16x16x32_bf16 v[40:43], v[168:171], v[184:187], v[40:43]
	v_mfma_f32_16x16x32_bf16 v[36:39], v[168:171], v[188:191], v[36:39]
	v_mfma_f32_16x16x32_bf16 v[32:35], v[168:171], v[192:195], v[32:35]
	v_mfma_f32_16x16x32_bf16 v[28:31], v[172:175], v[180:183], v[28:31]
	v_mfma_f32_16x16x32_bf16 v[24:27], v[172:175], v[184:187], v[24:27]
	v_mfma_f32_16x16x32_bf16 v[20:23], v[172:175], v[188:191], v[20:23]
	v_mfma_f32_16x16x32_bf16 v[16:19], v[172:175], v[192:195], v[16:19]
	v_mfma_f32_16x16x32_bf16 v[12:15], v[176:179], v[180:183], v[12:15]
	v_mfma_f32_16x16x32_bf16 v[8:11], v[176:179], v[184:187], v[8:11]
	v_mfma_f32_16x16x32_bf16 v[4:7], v[176:179], v[188:191], v[4:7]
	v_mfma_f32_16x16x32_bf16 v[0:3], v[176:179], v[192:195], v[0:3]
	ds_read_b128 v[180:183], v215 offset:32768
	ds_read_b128 v[184:187], v215 offset:34816
	ds_read_b128 v[188:191], v215 offset:36864
	ds_read_b128 v[192:195], v215 offset:38912
	s_waitcnt lgkmcnt(0)
; __device__ __forceinline__ f32x4 mfma16(bf16x8 a, bf16x8 b, f32x4 c) { return __builtin_amdgcn_mfma_f32_16x16x32_bf16(a, b, c, 0, 0, 0); }
; #define RAW_BARRIER() do { asm volatile("s_waitcnt lgkmcnt(0)" ::: "memory"); __builtin_amdgcn_s_barrier(); } while (0)
; #define GEMM_STEP(J, BUF, NBUF) do { asm volatile("s_waitcnt vmcnt(4)" ::: "memory"); RAW_BARRIER(); \
;     if ((J) + 2 < nk) gemm_issue(g, (J) + 2, NBUF, L); comp(BUF); } while (0)
; __device__ __forceinline__ void gemm_main(f32x4 (&acc)[4][4], const GemmOps& g, int K, u16* lds) {
;     ...
;   auto comp = [&](int buf) __attribute__((always_inline)) {
;     const char* sb = L + buf * GEMM_STAGE_B;
;     bf16x8 a[4], b[4];
; #pragma unroll
;     for (int i = 0; i < 4; ++i) a[i] = *(const bf16x8*)(sb + offA[i]);
; #pragma unroll
;     for (int j = 0; j < 4; ++j) b[j] = *(const bf16x8*)(sb + offB[j]);
; #pragma unroll
;     for (int i = 0; i < 4; ++i)
; #pragma unroll
;       for (int j = 0; j < 4; ++j) acc[i][j] = mfma16(a[i], b[j], acc[i][j]);
;   };
;   const int nk = K >> 5;
;     ...
;   int j = 0;
;   for (; j + 3 <= nk - 1; j += 3) {
;     GEMM_STEP(j, 0, 2);
;     GEMM_STEP(j + 1, 1, 0);
;     GEMM_STEP(j + 2, 2, 1);
;   }
;   GEMM_STEP(j, 0, 2);
;   asm volatile("s_waitcnt vmcnt(0)" ::: "memory");
;   RAW_BARRIER();
;   comp(1);
	v_mfma_f32_16x16x32_bf16 v[124:127], v[196:199], v[180:183], v[124:127]
	v_mfma_f32_16x16x32_bf16 v[120:123], v[196:199], v[184:187], v[120:123]
	v_mfma_f32_16x16x32_bf16 v[116:119], v[196:199], v[188:191], v[116:119]
	v_mfma_f32_16x16x32_bf16 v[48:51], v[196:199], v[192:195], v[48:51]
	v_mfma_f32_16x16x32_bf16 v[44:47], v[200:203], v[180:183], v[44:47]
	v_mfma_f32_16x16x32_bf16 v[40:43], v[200:203], v[184:187], v[40:43]
	v_mfma_f32_16x16x32_bf16 v[36:39], v[200:203], v[188:191], v[36:39]
	v_mfma_f32_16x16x32_bf16 v[32:35], v[200:203], v[192:195], v[32:35]
	v_mfma_f32_16x16x32_bf16 v[28:31], v[138:141], v[180:183], v[28:31]
	v_mfma_f32_16x16x32_bf16 v[24:27], v[138:141], v[184:187], v[24:27]
	v_mfma_f32_16x16x32_bf16 v[20:23], v[138:141], v[188:191], v[20:23]
	v_mfma_f32_16x16x32_bf16 v[16:19], v[138:141], v[192:195], v[16:19]
	v_mfma_f32_16x16x32_bf16 v[12:15], v[142:145], v[180:183], v[12:15]
	v_mfma_f32_16x16x32_bf16 v[8:11], v[142:145], v[184:187], v[8:11]
	v_mfma_f32_16x16x32_bf16 v[4:7], v[142:145], v[188:191], v[4:7]
	v_mfma_f32_16x16x32_bf16 v[0:3], v[142:145], v[192:195], v[0:3]
	s_sub_u32 s94, s94, 1
	s_cmp_lg_u32 s94, 0
	s_cbranch_scc1 .Lg4_k
	s_waitcnt vmcnt(0)
	s_barrier
	s_add_u32 s88, s88, 0x80
	s_addc_u32 s89, s89, 0
	s_add_u32 s90, s90, 0x80
	s_addc_u32 s91, s91, 0
	s_mov_b32 m0, s93
	ds_read_b128 v[164:167], v210 offset:0
	global_load_lds_dwordx4 v206, s[88:89]
	s_add_u32 m0, m0, 0x1000
	ds_read_b128 v[168:171], v210 offset:2048
	global_load_lds_dwordx4 v207, s[88:89]
	s_add_u32 m0, m0, 0x1000
	ds_read_b128 v[172:175], v210 offset:4096
	global_load_lds_dwordx4 v208, s[88:89]
	s_add_u32 m0, m0, 0x1000
	ds_read_b128 v[176:179], v210 offset:6144
	global_load_lds_dwordx4 v209, s[88:89]
	s_add_u32 m0, m0, 0x1000
	ds_read_b128 v[180:183], v212 offset:0
	global_load_lds_dwordx4 v206, s[90:91]
	s_add_u32 m0, m0, 0x1000
	ds_read_b128 v[184:187], v212 offset:2048
	global_load_lds_dwordx4 v207, s[90:91]
	s_add_u32 m0, m0, 0x1400
	ds_read_b128 v[188:191], v212 offset:4096
	global_load_lds_dwordx4 v208, s[90:91]
	s_add_u32 m0, m0, 0x1000
	ds_read_b128 v[192:195], v212 offset:6144
	global_load_lds_dwordx4 v209, s[90:91]
	ds_read_b128 v[196:199], v211 offset:0
	ds_read_b128 v[200:203], v211 offset:2048
	ds_read_b128 v[138:141], v211 offset:4096
	ds_read_b128 v[142:145], v211 offset:6144
	s_waitcnt lgkmcnt(4)
	v_mfma_f32_16x16x32_bf16 v[124:127], v[164:167], v[180:183], v[124:127]
	v_mfma_f32_16x16x32_bf16 v[120:123], v[164:167], v[184:187], v[120:123]
	v_mfma_f32_16x16x32_bf16 v[116:119], v[164:167], v[188:191], v[116:119]
	v_mfma_f32_16x16x32_bf16 v[48:51], v[164:167], v[192:195], v[48:51]
	v_mfma_f32_16x16x32_bf16 v[44:47], v[168:171], v[180:183], v[44:47]
	v_mfma_f32_16x16x32_bf16 v[40:43], v[168:171], v[184:187], v[40:43]
	v_mfma_f32_16x16x32_bf16 v[36:39], v[168:171], v[188:191], v[36:39]
	v_mfma_f32_16x16x32_bf16 v[32:35], v[168:171], v[192:195], v[32:35]
	v_mfma_f32_16x16x32_bf16 v[28:31], v[172:175], v[180:183], v[28:31]
	v_mfma_f32_16x16x32_bf16 v[24:27], v[172:175], v[184:187], v[24:27]
	v_mfma_f32_16x16x32_bf16 v[20:23], v[172:175], v[188:191], v[20:23]
	v_mfma_f32_16x16x32_bf16 v[16:19], v[172:175], v[192:195], v[16:19]
	v_mfma_f32_16x16x32_bf16 v[12:15], v[176:179], v[180:183], v[12:15]
	v_mfma_f32_16x16x32_bf16 v[8:11], v[176:179], v[184:187], v[8:11]
	v_mfma_f32_16x16x32_bf16 v[4:7], v[176:179], v[188:191], v[4:7]
	v_mfma_f32_16x16x32_bf16 v[0:3], v[176:179], v[192:195], v[0:3]
	ds_read_b128 v[180:183], v213 offset:0
	ds_read_b128 v[184:187], v213 offset:2048
	ds_read_b128 v[188:191], v213 offset:4096
	ds_read_b128 v[192:195], v213 offset:6144
	s_waitcnt lgkmcnt(0)
	v_mfma_f32_16x16x32_bf16 v[124:127], v[196:199], v[180:183], v[124:127]
	v_mfma_f32_16x16x32_bf16 v[120:123], v[196:199], v[184:187], v[120:123]
	v_mfma_f32_16x16x32_bf16 v[116:119], v[196:199], v[188:191], v[116:119]
	v_mfma_f32_16x16x32_bf16 v[48:51], v[196:199], v[192:195], v[48:51]
	v_mfma_f32_16x16x32_bf16 v[44:47], v[200:203], v[180:183], v[44:47]
	v_mfma_f32_16x16x32_bf16 v[40:43], v[200:203], v[184:187], v[40:43]
	v_mfma_f32_16x16x32_bf16 v[36:39], v[200:203], v[188:191], v[36:39]
	v_mfma_f32_16x16x32_bf16 v[32:35], v[200:203], v[192:195], v[32:35]
	v_mfma_f32_16x16x32_bf16 v[28:31], v[138:141], v[180:183], v[28:31]
	v_mfma_f32_16x16x32_bf16 v[24:27], v[138:141], v[184:187], v[24:27]
	v_mfma_f32_16x16x32_bf16 v[20:23], v[138:141], v[188:191], v[20:23]
	v_mfma_f32_16x16x32_bf16 v[16:19], v[138:141], v[192:195], v[16:19]
	v_mfma_f32_16x16x32_bf16 v[12:15], v[142:145], v[180:183], v[12:15]
	v_mfma_f32_16x16x32_bf16 v[8:11], v[142:145], v[184:187], v[8:11]
	v_mfma_f32_16x16x32_bf16 v[4:7], v[142:145], v[188:191], v[4:7]
	v_mfma_f32_16x16x32_bf16 v[0:3], v[142:145], v[192:195], v[0:3]
	s_waitcnt vmcnt(0)
	s_barrier
; __device__ __forceinline__ uint2 pack4v(f32x4 a) { uint2 r; r.x = pack2(a[0], a[1]); r.y = pack2(a[2], a[3]); return r; }
; __device__ __forceinline__ f32x4 mfma16(bf16x8 a, bf16x8 b, f32x4 c) { return __builtin_amdgcn_mfma_f32_16x16x32_bf16(a, b, c, 0, 0, 0); }
; #define ZERO_ACC(acc) zero_acc(acc)
; __device__ __forceinline__ void gemm_main(f32x4 (&acc)[4][4], const GemmOps& g, int K, u16* lds) {
;     ...
;   auto comp = [&](int buf) __attribute__((always_inline)) {
;     const char* sb = L + buf * GEMM_STAGE_B;
;     bf16x8 a[4], b[4];
; #pragma unroll
;     for (int i = 0; i < 4; ++i) a[i] = *(const bf16x8*)(sb + offA[i]);
; #pragma unroll
;     for (int j = 0; j < 4; ++j) b[j] = *(const bf16x8*)(sb + offB[j]);
; #pragma unroll
;     for (int i = 0; i < 4; ++i)
; #pragma unroll
;       for (int j = 0; j < 4; ++j) acc[i][j] = mfma16(a[i], b[j], acc[i][j]);
;   };
; __device__ void ph_gemm4(const P& p, u16* lds) {
;     ...
;   auto opsP = [&](int t) __attribute__((always_inline)) { return gemm_ops(p_Pb + (size_t)(t / NT) * 128 * 256, 256, p_WpT + (size_t)(t % NT) * 128 * 256, 256); };
;   auto opsG = [&](int t) __attribute__((always_inline)) { return gemm_ops(p_Abf + (size_t)(t / NT) * 128 * DM, DM, p_WgT + (size_t)(t % NT) * 128 * DM, DM); };
;   GemmOps g = opsP(it);
;   __syncthreads();
;   gemm_prologue(g, lds);
;   while (true) {
;     const int mt = it / NT, nt = it % NT;
;     f32x4 acc[4][4]; ZERO_ACC(acc);
;     gemm_main(acc, g, 256, lds);
;     __syncthreads();
;     g = opsG(it);
;     gemm_prologue(g, lds);
;     uint2 pp[4][4];
; #pragma unroll
;     for (int i = 0; i < 4; ++i)
; #pragma unroll
;       for (int j = 0; j < 4; ++j) pp[i][j] = pack4v(acc[i][j]);
;     ZERO_ACC(acc);
;     gemm_main(acc, g, DM, lds);
;     const int itn = it + gridDim.x; const bool more = itn < NTILES;
;     __syncthreads();
;     if (more) { g = opsP(itn); gemm_prologue(g, lds); }
	ds_read_b128 v[164:167], v210 offset:32768
	ds_read_b128 v[168:171], v210 offset:34816
	ds_read_b128 v[172:175], v210 offset:36864
	ds_read_b128 v[176:179], v210 offset:38912
	ds_read_b128 v[180:183], v214 offset:32768
	ds_read_b128 v[184:187], v214 offset:34816
	ds_read_b128 v[188:191], v214 offset:36864
	ds_read_b128 v[192:195], v214 offset:38912
	ds_read_b128 v[196:199], v211 offset:32768
	ds_read_b128 v[200:203], v211 offset:34816
	ds_read_b128 v[138:141], v211 offset:36864
	ds_read_b128 v[142:145], v211 offset:38912
	s_waitcnt lgkmcnt(4)
	v_mfma_f32_16x16x32_bf16 v[124:127], v[164:167], v[180:183], v[124:127]
	v_mfma_f32_16x16x32_bf16 v[120:123], v[164:167], v[184:187], v[120:123]
	v_mfma_f32_16x16x32_bf16 v[116:119], v[164:167], v[188:191], v[116:119]
	v_mfma_f32_16x16x32_bf16 v[48:51], v[164:167], v[192:195], v[48:51]
	v_mfma_f32_16x16x32_bf16 v[44:47], v[168:171], v[180:183], v[44:47]
	v_mfma_f32_16x16x32_bf16 v[40:43], v[168:171], v[184:187], v[40:43]
	v_mfma_f32_16x16x32_bf16 v[36:39], v[168:171], v[188:191], v[36:39]
	v_mfma_f32_16x16x32_bf16 v[32:35], v[168:171], v[192:195], v[32:35]
	v_mfma_f32_16x16x32_bf16 v[28:31], v[172:175], v[180:183], v[28:31]
	v_mfma_f32_16x16x32_bf16 v[24:27], v[172:175], v[184:187], v[24:27]
	v_mfma_f32_16x16x32_bf16 v[20:23], v[172:175], v[188:191], v[20:23]
	v_mfma_f32_16x16x32_bf16 v[16:19], v[172:175], v[192:195], v[16:19]
	v_mfma_f32_16x16x32_bf16 v[12:15], v[176:179], v[180:183], v[12:15]
	v_mfma_f32_16x16x32_bf16 v[8:11], v[176:179], v[184:187], v[8:11]
	v_mfma_f32_16x16x32_bf16 v[4:7], v[176:179], v[188:191], v[4:7]
	v_mfma_f32_16x16x32_bf16 v[0:3], v[176:179], v[192:195], v[0:3]
	ds_read_b128 v[180:183], v215 offset:32768
	ds_read_b128 v[184:187], v215 offset:34816
	ds_read_b128 v[188:191], v215 offset:36864
	ds_read_b128 v[192:195], v215 offset:38912
	s_waitcnt lgkmcnt(0)
	v_mfma_f32_16x16x32_bf16 v[124:127], v[196:199], v[180:183], v[124:127]
	v_mfma_f32_16x16x32_bf16 v[120:123], v[196:199], v[184:187], v[120:123]
	v_mfma_f32_16x16x32_bf16 v[116:119], v[196:199], v[188:191], v[116:119]
	v_mfma_f32_16x16x32_bf16 v[48:51], v[196:199], v[192:195], v[48:51]
	v_mfma_f32_16x16x32_bf16 v[44:47], v[200:203], v[180:183], v[44:47]
	v_mfma_f32_16x16x32_bf16 v[40:43], v[200:203], v[184:187], v[40:43]
	v_mfma_f32_16x16x32_bf16 v[36:39], v[200:203], v[188:191], v[36:39]
	v_mfma_f32_16x16x32_bf16 v[32:35], v[200:203], v[192:195], v[32:35]
	v_mfma_f32_16x16x32_bf16 v[28:31], v[138:141], v[180:183], v[28:31]
	v_mfma_f32_16x16x32_bf16 v[24:27], v[138:141], v[184:187], v[24:27]
	v_mfma_f32_16x16x32_bf16 v[20:23], v[138:141], v[188:191], v[20:23]
	v_mfma_f32_16x16x32_bf16 v[16:19], v[138:141], v[192:195], v[16:19]
	v_mfma_f32_16x16x32_bf16 v[12:15], v[142:145], v[180:183], v[12:15]
	v_mfma_f32_16x16x32_bf16 v[8:11], v[142:145], v[184:187], v[8:11]
	v_mfma_f32_16x16x32_bf16 v[4:7], v[142:145], v[188:191], v[4:7]
	v_mfma_f32_16x16x32_bf16 v[0:3], v[142:145], v[192:195], v[0:3]
	s_waitcnt lgkmcnt(0)
	s_barrier
	s_nop 7
	v_readlane_b32 s4, v228, 10
	s_add_i32 s69, s69, s4
	s_cmpk_gt_i32 s69, 0x83f
	s_cselect_b64 s[48:49], -1, 0
	s_and_b64 vcc, exec, s[48:49]
	v_readlane_b32 s5, v228, 11
	s_cbranch_vccnz .LBB0_1112
	s_and_b32 s81, s69, 7
	s_lshr_b32 s82, s69, 3
	s_lshr_b32 s83, s82, 6
	s_and_b32 s84, s82, 63
	s_cmp_lt_u32 s83, 4
	s_cselect_b32 s85, 3, 0
	s_cselect_b32 s86, 7, 0
	s_lshr_b32 s87, s84, s85
	s_and_b32 s84, s84, s86
	s_lshl_b32 s83, s83, 3
	s_add_u32 s83, s83, s84
	s_mul_i32 s81, s81, 33
	s_add_u32 s81, s81, s83
	s_mul_i32 s81, s81, 8
	s_add_u32 s80, s81, s87
	s_ashr_i32 s1, s80, 31
	s_lshr_b32 s1, s1, 29
	s_add_i32 s1, s80, s1
	s_ashr_i32 s4, s1, 3
	s_ashr_i32 s5, s4, 31
	s_lshl_b64 s[4:5], s[4:5], 16
	s_add_u32 s4, s33, s4
	v_mov_b32_e32 v128, v220
	v_mov_b32_e32 v130, v220
	s_addc_u32 s5, s45, s5
	s_and_b32 s1, s1, -8
	s_sub_i32 s6, s80, s1
	v_lshrrev_b32_e32 v131, 2, v128
	v_ashrrev_i32_e32 v130, 2, v130
	s_ashr_i32 s7, s6, 31
	v_bfi_b32 v130, -16, v130, v131
	s_lshl_b64 s[6:7], s[6:7], 16
	v_add_u32_e32 v132, 64, v130
	v_lshrrev_b32_e32 v133, 4, v128
	s_add_u32 s6, s47, s6
	v_ashrrev_i32_e32 v131, 31, v130
	v_xor_b32_e32 v128, v133, v128
	v_ashrrev_i32_e32 v133, 31, v132
	s_addc_u32 s7, s52, s7
	v_lshlrev_b64 v[134:135], 9, v[130:131]
	v_lshlrev_b32_e32 v128, 4, v128
	v_lshlrev_b64 v[136:137], 9, v[132:133]
	v_lshl_add_u64 v[130:131], s[4:5], 0, v[134:135]
	v_and_b32_e32 v128, 48, v128
	v_lshl_add_u64 v[132:133], s[4:5], 0, v[136:137]
	v_lshl_add_u64 v[134:135], s[6:7], 0, v[134:135]
	v_lshl_add_u64 v[136:137], s[6:7], 0, v[136:137]
	v_lshl_add_u64 v[130:131], v[130:131], 0, v[128:129]
	v_lshl_add_u64 v[132:133], v[132:133], 0, v[128:129]
	v_lshl_add_u64 v[134:135], v[134:135], 0, v[128:129]
	v_lshl_add_u64 v[136:137], v[136:137], 0, v[128:129]
	v_mov_b32_e32 v128, v220
	s_nop 0
	v_lshlrev_b32_e32 v128, 4, v128
	v_and_b32_e32 v128, 0xfffffc00, v128
	v_add_u32_e32 v138, 0x1000, v128
	v_readfirstlane_b32 s1, v128
	s_mov_b32 m0, s1
	v_readfirstlane_b32 s1, v138
	v_add_u32_e32 v138, 0x2000, v128
	global_load_lds_dwordx4 v[130:131], off
	s_mov_b32 m0, s1
	v_readfirstlane_b32 s1, v138
	v_add_u32_e32 v128, 0x3000, v128
	global_load_lds_dwordx4 v[132:133], off
	s_mov_b32 m0, s1
	v_readfirstlane_b32 s1, v128
	global_load_lds_dwordx4 v[134:135], off
	s_mov_b32 m0, s1
	v_mov_b32_e32 v128, v220
	global_load_lds_dwordx4 v[136:137], off
	v_lshl_add_u64 v[138:139], v[130:131], 0, 64
	v_lshlrev_b32_e32 v128, 4, v128
	v_and_b32_e32 v128, 0xfffffc00, v128
	v_add_u32_e32 v140, 0x4000, v128
	s_nop 0
	v_readfirstlane_b32 s1, v140
	v_add_u32_e32 v140, 0x5000, v128
	s_mov_b32 m0, s1
	v_readfirstlane_b32 s1, v140
	v_add_u32_e32 v140, 0x6000, v128
	global_load_lds_dwordx4 v[138:139], off
	v_lshl_add_u64 v[138:139], v[132:133], 0, 64
	s_mov_b32 m0, s1
	v_readfirstlane_b32 s1, v140
	v_add_u32_e32 v128, 0x7000, v128
	global_load_lds_dwordx4 v[138:139], off
	v_lshl_add_u64 v[138:139], v[134:135], 0, 64
	s_mov_b32 m0, s1
	v_readfirstlane_b32 s1, v128
	global_load_lds_dwordx4 v[138:139], off
	v_lshl_add_u64 v[138:139], v[136:137], 0, 64
	s_mov_b32 m0, s1
	s_nop 0
	global_load_lds_dwordx4 v[138:139], off
	s_branch .LBB0_1112
